# attn merge: row-half dwordx4 loads/stores + permlane32_swap redistribution (12 instead of 24 bf16 loads, 4 instead of 8 stores), loads hoisted in 2 rounds
# speedup vs baseline: 1.0141x; 1.0131x over previous
; DI unsigned pk2(float lo, float hi) { const f32x2_t v = {lo, hi}; const bf16x2_t b = __builtin_convertvector(v, bf16x2_t); return __builtin_bit_cast(unsigned, b); }
; DI float sigmoidf_(float x) { return __builtin_amdgcn_rcpf(1.f + __builtin_amdgcn_exp2f(fminf(-x * LOG2E, 126.f))); }
; template <int DV>
; DI void attn_unit(const int wv, const Args& A, LAS unsigned char* lds, int b, int g, int qb, int dry) {
;     ...
;         const float sc = g2 / fmaxf(l, 1e-30f);
; #pragma unroll
;         for (int i = 0; i < 16; ++i) { O[0][i] = ypark[i * 64] + sc * O[0][i]; O[1][i] = ypark[(16 + i) * 64] + sc * O[1][i]; }
;     ...
;         bf16* Yb = (bf16*)A.out; const bf16* GMA = (const bf16*)(ws + WS_GMA);
; #pragma unroll
;         for (int mt = 0; mt < 2; ++mt)
; #pragma unroll
;             for (int v = 0; v < 4; ++v) {
;                 const size_t idx = tokrow * DM + head * 64 + mt * 32 + 8 * v + 4 * c.h;
;                 const u32x2 yr = *(const u32x2*)(Yb + idx), gm = *(const u32x2*)(GMA + idx), ct = *(const u32x2*)((const bf16*)(ws + WS_CT) + idx);
;                 const f32x4 cr = *(const f32x4*)((const float*)(ws + WS_CARRY) + ((size_t)b * 64 + (c.t >> 7)) * DM + head * 64 + mt * 32 + 8 * v + 4 * c.h);
;                 const float o0 = bflo(yr.x) + bflo(ct.x) * cr[0] + sigmoidf_(bflo(gm.x)) * O[mt][4 * v], o1 = bfhi(yr.x) + bfhi(ct.x) * cr[1] + sigmoidf_(bfhi(gm.x)) * O[mt][4 * v + 1];
;                 const float o2 = bflo(yr.y) + bflo(ct.y) * cr[2] + sigmoidf_(bflo(gm.y)) * O[mt][4 * v + 2], o3 = bfhi(yr.y) + bfhi(ct.y) * cr[3] + sigmoidf_(bfhi(gm.y)) * O[mt][4 * v + 3];
;                 *(u32x2*)(((dry & 1) ? (bf16*)(ws + 832 * MiB) : Yb) + idx) = (u32x2){pk2(o0, o1), pk2(o2, o3)};
;             }
.LBB0_789:
	s_waitcnt vmcnt(0)
	v_or_b32_e32 v0, v211, v154
	v_or_b32_e32 v164, v0, v164
	v_mad_u32_u24 v10, v154, 7, v164
	v_mov_b32_e32 v11, v165
	v_lshlrev_b64 v[10:11], 1, v[10:11]
	v_readlane_b32 s8, v254, 2
	v_readlane_b32 s9, v254, 3
	v_lshl_add_u64 v[4:5], s[64:65], 0, v[10:11]
	v_lshl_add_u64 v[6:7], s[66:67], 0, v[10:11]
	s_nop 0
	v_lshl_add_u64 v[0:1], s[8:9], 0, v[10:11]
	s_lshr_b32 s62, s91, 7
	s_lshl_b32 s6, s45, 18
	v_readlane_b32 s7, v254, 59
	s_nop 3
	s_add_u32 s8, s7, s6
	s_addc_u32 s9, s89, 0
	s_lshl_b64 s[6:7], s[62:63], 12
	s_add_u32 s6, s8, s6
	v_lshlrev_b32_e32 v8, 2, v211
	v_mov_b32_e32 v9, v2
	s_addc_u32 s7, s9, s7
	v_mov_b32_e32 v155, v2
	v_lshl_add_u64 v[8:9], s[6:7], 0, v[8:9]
	v_lshl_add_u64 v[12:13], v[154:155], 2, v[8:9]
	global_load_dwordx4 v[112:115], v[4:5], off
	global_load_dwordx4 v[116:119], v[6:7], off
	global_load_dwordx4 v[120:123], v[0:1], off
	global_load_dwordx4 v[232:235], v[12:13], off
	global_load_dwordx4 v[236:239], v[12:13], off offset:128
	global_load_dwordx4 v[124:127], v[4:5], off offset:16
	global_load_dwordx4 v[128:131], v[6:7], off offset:16
	global_load_dwordx4 v[132:135], v[0:1], off offset:16
	global_load_dwordx4 v[240:243], v[12:13], off offset:32
	global_load_dwordx4 v[244:247], v[12:13], off offset:160
	v_lshlrev_b32_e32 v3, 16, v163
	v_mul_f32_e32 v3, 0xbfb8aa3b, v3
	v_min_f32_e32 v3, 0x42fc0000, v3
	v_exp_f32_e32 v3, v3
	v_readlane_b32 s10, v254, 4
	v_readlane_b32 s11, v254, 5
	v_add_f32_e32 v3, 1.0, v3
	v_rcp_f32_e32 v3, v3
	s_nop 0
	v_div_scale_f32 v8, s[6:7], v32, v32, v3
	v_rcp_f32_e32 v9, v8
	v_div_scale_f32 v33, vcc, v3, v32, v3
	s_mov_b64 s[6:7], 0
	v_fma_f32 v48, -v8, v9, 1.0
	v_fmac_f32_e32 v9, v48, v9
	v_mul_f32_e32 v48, v33, v9
	v_fma_f32 v49, -v8, v48, v33
	v_fmac_f32_e32 v48, v49, v9
	v_fma_f32 v8, -v8, v48, v33
	v_div_fmas_f32 v8, v8, v9, v48
	v_div_fixup_f32 v8, v8, v32, v3
	s_waitcnt vmcnt(5)
	v_permlane32_swap_b32 v112, v114
	v_permlane32_swap_b32 v113, v115
	v_permlane32_swap_b32 v116, v118
	v_permlane32_swap_b32 v117, v119
	v_permlane32_swap_b32 v120, v122
	v_permlane32_swap_b32 v121, v123
	ds_read2st64_b32 v[40:41], v137 offset1:1
	ds_read2st64_b32 v[42:43], v137 offset0:2 offset1:3
	v_lshlrev_b32_e32 v3, 16, v112
	v_and_b32_e32 v9, 0xffff0000, v112
	v_lshlrev_b32_e32 v38, 16, v113
	v_and_b32_e32 v39, 0xffff0000, v113
	v_mul_f32_e32 v3, 0xbfb8aa3b, v3
	v_mul_f32_e32 v9, 0xbfb8aa3b, v9
	v_mul_f32_e32 v38, 0xbfb8aa3b, v38
	v_mul_f32_e32 v39, 0xbfb8aa3b, v39
	v_min_f32_e32 v3, 0x42fc0000, v3
	v_min_f32_e32 v9, 0x42fc0000, v9
	v_min_f32_e32 v38, 0x42fc0000, v38
	v_min_f32_e32 v39, 0x42fc0000, v39
	v_exp_f32_e32 v3, v3
	v_exp_f32_e32 v9, v9
	v_exp_f32_e32 v38, v38
	v_exp_f32_e32 v39, v39
	v_add_f32_e32 v3, 1.0, v3
	v_add_f32_e32 v9, 1.0, v9
	v_add_f32_e32 v50, 1.0, v38
	v_add_f32_e32 v51, 1.0, v39
	v_rcp_f32_e32 v38, v3
	v_rcp_f32_e32 v39, v9
	v_rcp_f32_e32 v50, v50
	v_rcp_f32_e32 v51, v51
	v_lshlrev_b32_e32 v48, 16, v116
	v_and_b32_e32 v49, 0xffff0000, v116
	v_lshlrev_b32_e32 v36, 16, v117
	v_and_b32_e32 v37, 0xffff0000, v117
	v_lshlrev_b32_e32 v44, 16, v120
	v_and_b32_e32 v45, 0xffff0000, v120
	v_lshlrev_b32_e32 v46, 16, v121
	v_and_b32_e32 v47, 0xffff0000, v121
	s_waitcnt lgkmcnt(0)
	v_pk_fma_f32 v[34:35], v[8:9], v[64:65], v[40:41] op_sel_hi:[0,1,1]
	v_pk_fma_f32 v[40:41], v[8:9], v[66:67], v[42:43] op_sel_hi:[0,1,1]
	v_pk_fma_f32 v[232:233], v[232:233], v[48:49], v[44:45]
	v_pk_fma_f32 v[234:235], v[234:235], v[36:37], v[46:47]
	v_pk_fma_f32 v[232:233], v[34:35], v[38:39], v[232:233]
	v_pk_fma_f32 v[234:235], v[40:41], v[50:51], v[234:235]
	v_cvt_pk_bf16_f32 v248, v232, v233
	v_cvt_pk_bf16_f32 v249, v234, v235
	ds_read2st64_b32 v[40:41], v137 offset0:16 offset1:17
	ds_read2st64_b32 v[42:43], v137 offset0:18 offset1:19
	v_lshlrev_b32_e32 v3, 16, v114
	v_and_b32_e32 v9, 0xffff0000, v114
	v_lshlrev_b32_e32 v38, 16, v115
	v_and_b32_e32 v39, 0xffff0000, v115
	v_mul_f32_e32 v3, 0xbfb8aa3b, v3
	v_mul_f32_e32 v9, 0xbfb8aa3b, v9
	v_mul_f32_e32 v38, 0xbfb8aa3b, v38
	v_mul_f32_e32 v39, 0xbfb8aa3b, v39
	v_min_f32_e32 v3, 0x42fc0000, v3
	v_min_f32_e32 v9, 0x42fc0000, v9
	v_min_f32_e32 v38, 0x42fc0000, v38
	v_min_f32_e32 v39, 0x42fc0000, v39
	v_exp_f32_e32 v3, v3
	v_exp_f32_e32 v9, v9
	v_exp_f32_e32 v38, v38
	v_exp_f32_e32 v39, v39
	v_add_f32_e32 v3, 1.0, v3
	v_add_f32_e32 v9, 1.0, v9
	v_add_f32_e32 v50, 1.0, v38
	v_add_f32_e32 v51, 1.0, v39
	v_rcp_f32_e32 v38, v3
	v_rcp_f32_e32 v39, v9
	v_rcp_f32_e32 v50, v50
	v_rcp_f32_e32 v51, v51
	v_lshlrev_b32_e32 v48, 16, v118
	v_and_b32_e32 v49, 0xffff0000, v118
	v_lshlrev_b32_e32 v36, 16, v119
	v_and_b32_e32 v37, 0xffff0000, v119
	v_lshlrev_b32_e32 v44, 16, v122
	v_and_b32_e32 v45, 0xffff0000, v122
	v_lshlrev_b32_e32 v46, 16, v123
	v_and_b32_e32 v47, 0xffff0000, v123
	s_waitcnt lgkmcnt(0)
	v_pk_fma_f32 v[34:35], v[8:9], v[16:17], v[40:41] op_sel_hi:[0,1,1]
	v_pk_fma_f32 v[40:41], v[8:9], v[18:19], v[42:43] op_sel_hi:[0,1,1]
	v_pk_fma_f32 v[236:237], v[236:237], v[48:49], v[44:45]
	v_pk_fma_f32 v[238:239], v[238:239], v[36:37], v[46:47]
	v_pk_fma_f32 v[236:237], v[34:35], v[38:39], v[236:237]
	v_pk_fma_f32 v[238:239], v[40:41], v[50:51], v[238:239]
	v_cvt_pk_bf16_f32 v250, v236, v237
	v_cvt_pk_bf16_f32 v251, v238, v239
	s_nop 1
	v_permlane32_swap_b32 v248, v250
	v_permlane32_swap_b32 v249, v251
	global_store_dwordx4 v[0:1], v[248:251], off
	global_load_dwordx4 v[112:115], v[4:5], off offset:32
	global_load_dwordx4 v[116:119], v[6:7], off offset:32
	global_load_dwordx4 v[120:123], v[0:1], off offset:32
	global_load_dwordx4 v[232:235], v[12:13], off offset:64
	global_load_dwordx4 v[236:239], v[12:13], off offset:192
	s_waitcnt vmcnt(6)
; DI unsigned pk2(float lo, float hi) { const f32x2_t v = {lo, hi}; const bf16x2_t b = __builtin_convertvector(v, bf16x2_t); return __builtin_bit_cast(unsigned, b); }
; DI float sigmoidf_(float x) { return __builtin_amdgcn_rcpf(1.f + __builtin_amdgcn_exp2f(fminf(-x * LOG2E, 126.f))); }
; template <int DV>
; DI void attn_unit(const int wv, const Args& A, LAS unsigned char* lds, int b, int g, int qb, int dry) {
;     ...
;         bf16* Yb = (bf16*)A.out; const bf16* GMA = (const bf16*)(ws + WS_GMA);
; #pragma unroll
;         for (int mt = 0; mt < 2; ++mt)
; #pragma unroll
;             for (int v = 0; v < 4; ++v) {
;                 const size_t idx = tokrow * DM + head * 64 + mt * 32 + 8 * v + 4 * c.h;
;                 const u32x2 yr = *(const u32x2*)(Yb + idx), gm = *(const u32x2*)(GMA + idx), ct = *(const u32x2*)((const bf16*)(ws + WS_CT) + idx);
;                 const f32x4 cr = *(const f32x4*)((const float*)(ws + WS_CARRY) + ((size_t)b * 64 + (c.t >> 7)) * DM + head * 64 + mt * 32 + 8 * v + 4 * c.h);
;                 const float o0 = bflo(yr.x) + bflo(ct.x) * cr[0] + sigmoidf_(bflo(gm.x)) * O[mt][4 * v], o1 = bfhi(yr.x) + bfhi(ct.x) * cr[1] + sigmoidf_(bfhi(gm.x)) * O[mt][4 * v + 1];
;                 const float o2 = bflo(yr.y) + bflo(ct.y) * cr[2] + sigmoidf_(bflo(gm.y)) * O[mt][4 * v + 2], o3 = bfhi(yr.y) + bfhi(ct.y) * cr[3] + sigmoidf_(bfhi(gm.y)) * O[mt][4 * v + 3];
;                 *(u32x2*)(((dry & 1) ? (bf16*)(ws + 832 * MiB) : Yb) + idx) = (u32x2){pk2(o0, o1), pk2(o2, o3)};
;             }
	v_permlane32_swap_b32 v124, v126
	v_permlane32_swap_b32 v125, v127
	v_permlane32_swap_b32 v128, v130
	v_permlane32_swap_b32 v129, v131
	v_permlane32_swap_b32 v132, v134
	v_permlane32_swap_b32 v133, v135
	ds_read2st64_b32 v[40:41], v137 offset0:4 offset1:5
	ds_read2st64_b32 v[42:43], v137 offset0:6 offset1:7
	v_lshlrev_b32_e32 v3, 16, v124
	v_and_b32_e32 v9, 0xffff0000, v124
	v_lshlrev_b32_e32 v38, 16, v125
	v_and_b32_e32 v39, 0xffff0000, v125
	v_mul_f32_e32 v3, 0xbfb8aa3b, v3
	v_mul_f32_e32 v9, 0xbfb8aa3b, v9
	v_mul_f32_e32 v38, 0xbfb8aa3b, v38
	v_mul_f32_e32 v39, 0xbfb8aa3b, v39
	v_min_f32_e32 v3, 0x42fc0000, v3
	v_min_f32_e32 v9, 0x42fc0000, v9
	v_min_f32_e32 v38, 0x42fc0000, v38
	v_min_f32_e32 v39, 0x42fc0000, v39
	v_exp_f32_e32 v3, v3
	v_exp_f32_e32 v9, v9
	v_exp_f32_e32 v38, v38
	v_exp_f32_e32 v39, v39
	v_add_f32_e32 v3, 1.0, v3
	v_add_f32_e32 v9, 1.0, v9
	v_add_f32_e32 v50, 1.0, v38
	v_add_f32_e32 v51, 1.0, v39
	v_rcp_f32_e32 v38, v3
	v_rcp_f32_e32 v39, v9
	v_rcp_f32_e32 v50, v50
	v_rcp_f32_e32 v51, v51
	v_lshlrev_b32_e32 v48, 16, v128
	v_and_b32_e32 v49, 0xffff0000, v128
	v_lshlrev_b32_e32 v36, 16, v129
	v_and_b32_e32 v37, 0xffff0000, v129
	v_lshlrev_b32_e32 v44, 16, v132
	v_and_b32_e32 v45, 0xffff0000, v132
	v_lshlrev_b32_e32 v46, 16, v133
	v_and_b32_e32 v47, 0xffff0000, v133
	s_waitcnt lgkmcnt(0)
	v_pk_fma_f32 v[34:35], v[8:9], v[68:69], v[40:41] op_sel_hi:[0,1,1]
	v_pk_fma_f32 v[40:41], v[8:9], v[70:71], v[42:43] op_sel_hi:[0,1,1]
	v_pk_fma_f32 v[240:241], v[240:241], v[48:49], v[44:45]
	v_pk_fma_f32 v[242:243], v[242:243], v[36:37], v[46:47]
	v_pk_fma_f32 v[240:241], v[34:35], v[38:39], v[240:241]
	v_pk_fma_f32 v[242:243], v[40:41], v[50:51], v[242:243]
	v_cvt_pk_bf16_f32 v248, v240, v241
	v_cvt_pk_bf16_f32 v249, v242, v243
	ds_read2st64_b32 v[40:41], v137 offset0:20 offset1:21
	ds_read2st64_b32 v[42:43], v137 offset0:22 offset1:23
	v_lshlrev_b32_e32 v3, 16, v126
	v_and_b32_e32 v9, 0xffff0000, v126
	v_lshlrev_b32_e32 v38, 16, v127
	v_and_b32_e32 v39, 0xffff0000, v127
	v_mul_f32_e32 v3, 0xbfb8aa3b, v3
	v_mul_f32_e32 v9, 0xbfb8aa3b, v9
	v_mul_f32_e32 v38, 0xbfb8aa3b, v38
	v_mul_f32_e32 v39, 0xbfb8aa3b, v39
	v_min_f32_e32 v3, 0x42fc0000, v3
	v_min_f32_e32 v9, 0x42fc0000, v9
	v_min_f32_e32 v38, 0x42fc0000, v38
	v_min_f32_e32 v39, 0x42fc0000, v39
	v_exp_f32_e32 v3, v3
	v_exp_f32_e32 v9, v9
	v_exp_f32_e32 v38, v38
	v_exp_f32_e32 v39, v39
	v_add_f32_e32 v3, 1.0, v3
	v_add_f32_e32 v9, 1.0, v9
	v_add_f32_e32 v50, 1.0, v38
	v_add_f32_e32 v51, 1.0, v39
	v_rcp_f32_e32 v38, v3
	v_rcp_f32_e32 v39, v9
	v_rcp_f32_e32 v50, v50
	v_rcp_f32_e32 v51, v51
	v_lshlrev_b32_e32 v48, 16, v130
	v_and_b32_e32 v49, 0xffff0000, v130
	v_lshlrev_b32_e32 v36, 16, v131
	v_and_b32_e32 v37, 0xffff0000, v131
	v_lshlrev_b32_e32 v44, 16, v134
	v_and_b32_e32 v45, 0xffff0000, v134
	v_lshlrev_b32_e32 v46, 16, v135
	v_and_b32_e32 v47, 0xffff0000, v135
	s_waitcnt lgkmcnt(0)
	v_pk_fma_f32 v[34:35], v[8:9], v[20:21], v[40:41] op_sel_hi:[0,1,1]
	v_pk_fma_f32 v[40:41], v[8:9], v[22:23], v[42:43] op_sel_hi:[0,1,1]
	v_pk_fma_f32 v[244:245], v[244:245], v[48:49], v[44:45]
	v_pk_fma_f32 v[246:247], v[246:247], v[36:37], v[46:47]
	v_pk_fma_f32 v[244:245], v[34:35], v[38:39], v[244:245]
	v_pk_fma_f32 v[246:247], v[40:41], v[50:51], v[246:247]
	v_cvt_pk_bf16_f32 v250, v244, v245
	v_cvt_pk_bf16_f32 v251, v246, v247
	s_nop 1
	v_permlane32_swap_b32 v248, v250
	v_permlane32_swap_b32 v249, v251
	global_store_dwordx4 v[0:1], v[248:251], off offset:16
	global_load_dwordx4 v[124:127], v[4:5], off offset:48
	global_load_dwordx4 v[128:131], v[6:7], off offset:48
	global_load_dwordx4 v[132:135], v[0:1], off offset:48
	global_load_dwordx4 v[240:243], v[12:13], off offset:96
	global_load_dwordx4 v[244:247], v[12:13], off offset:224
	s_waitcnt vmcnt(6)
	v_permlane32_swap_b32 v112, v114
	v_permlane32_swap_b32 v113, v115
	v_permlane32_swap_b32 v116, v118
	v_permlane32_swap_b32 v117, v119
	v_permlane32_swap_b32 v120, v122
	v_permlane32_swap_b32 v121, v123
	ds_read2st64_b32 v[40:41], v137 offset0:8 offset1:9
	ds_read2st64_b32 v[42:43], v137 offset0:10 offset1:11
	v_lshlrev_b32_e32 v3, 16, v112
	v_and_b32_e32 v9, 0xffff0000, v112
	v_lshlrev_b32_e32 v38, 16, v113
	v_and_b32_e32 v39, 0xffff0000, v113
	v_mul_f32_e32 v3, 0xbfb8aa3b, v3
	v_mul_f32_e32 v9, 0xbfb8aa3b, v9
	v_mul_f32_e32 v38, 0xbfb8aa3b, v38
	v_mul_f32_e32 v39, 0xbfb8aa3b, v39
	v_min_f32_e32 v3, 0x42fc0000, v3
	v_min_f32_e32 v9, 0x42fc0000, v9
	v_min_f32_e32 v38, 0x42fc0000, v38
	v_min_f32_e32 v39, 0x42fc0000, v39
	v_exp_f32_e32 v3, v3
	v_exp_f32_e32 v9, v9
	v_exp_f32_e32 v38, v38
	v_exp_f32_e32 v39, v39
	v_add_f32_e32 v3, 1.0, v3
	v_add_f32_e32 v9, 1.0, v9
	v_add_f32_e32 v50, 1.0, v38
	v_add_f32_e32 v51, 1.0, v39
	v_rcp_f32_e32 v38, v3
	v_rcp_f32_e32 v39, v9
	v_rcp_f32_e32 v50, v50
	v_rcp_f32_e32 v51, v51
	v_lshlrev_b32_e32 v48, 16, v116
	v_and_b32_e32 v49, 0xffff0000, v116
	v_lshlrev_b32_e32 v36, 16, v117
	v_and_b32_e32 v37, 0xffff0000, v117
	v_lshlrev_b32_e32 v44, 16, v120
	v_and_b32_e32 v45, 0xffff0000, v120
	v_lshlrev_b32_e32 v46, 16, v121
	v_and_b32_e32 v47, 0xffff0000, v121
	s_waitcnt lgkmcnt(0)
; DI unsigned pk2(float lo, float hi) { const f32x2_t v = {lo, hi}; const bf16x2_t b = __builtin_convertvector(v, bf16x2_t); return __builtin_bit_cast(unsigned, b); }
; DI float sigmoidf_(float x) { return __builtin_amdgcn_rcpf(1.f + __builtin_amdgcn_exp2f(fminf(-x * LOG2E, 126.f))); }
; template <int DV>
; DI void attn_unit(const int wv, const Args& A, LAS unsigned char* lds, int b, int g, int qb, int dry) {
;     ...
;         bf16* Yb = (bf16*)A.out; const bf16* GMA = (const bf16*)(ws + WS_GMA);
; #pragma unroll
;         for (int mt = 0; mt < 2; ++mt)
; #pragma unroll
;             for (int v = 0; v < 4; ++v) {
;                 const size_t idx = tokrow * DM + head * 64 + mt * 32 + 8 * v + 4 * c.h;
;                 const u32x2 yr = *(const u32x2*)(Yb + idx), gm = *(const u32x2*)(GMA + idx), ct = *(const u32x2*)((const bf16*)(ws + WS_CT) + idx);
;                 const f32x4 cr = *(const f32x4*)((const float*)(ws + WS_CARRY) + ((size_t)b * 64 + (c.t >> 7)) * DM + head * 64 + mt * 32 + 8 * v + 4 * c.h);
;                 const float o0 = bflo(yr.x) + bflo(ct.x) * cr[0] + sigmoidf_(bflo(gm.x)) * O[mt][4 * v], o1 = bfhi(yr.x) + bfhi(ct.x) * cr[1] + sigmoidf_(bfhi(gm.x)) * O[mt][4 * v + 1];
;                 const float o2 = bflo(yr.y) + bflo(ct.y) * cr[2] + sigmoidf_(bflo(gm.y)) * O[mt][4 * v + 2], o3 = bfhi(yr.y) + bfhi(ct.y) * cr[3] + sigmoidf_(bfhi(gm.y)) * O[mt][4 * v + 3];
;                 *(u32x2*)(((dry & 1) ? (bf16*)(ws + 832 * MiB) : Yb) + idx) = (u32x2){pk2(o0, o1), pk2(o2, o3)};
;             }
	v_pk_fma_f32 v[34:35], v[8:9], v[72:73], v[40:41] op_sel_hi:[0,1,1]
	v_pk_fma_f32 v[40:41], v[8:9], v[74:75], v[42:43] op_sel_hi:[0,1,1]
	v_pk_fma_f32 v[232:233], v[232:233], v[48:49], v[44:45]
	v_pk_fma_f32 v[234:235], v[234:235], v[36:37], v[46:47]
	v_pk_fma_f32 v[232:233], v[34:35], v[38:39], v[232:233]
	v_pk_fma_f32 v[234:235], v[40:41], v[50:51], v[234:235]
	v_cvt_pk_bf16_f32 v248, v232, v233
	v_cvt_pk_bf16_f32 v249, v234, v235
	ds_read2st64_b32 v[40:41], v137 offset0:24 offset1:25
	ds_read2st64_b32 v[42:43], v137 offset0:26 offset1:27
	v_lshlrev_b32_e32 v3, 16, v114
	v_and_b32_e32 v9, 0xffff0000, v114
	v_lshlrev_b32_e32 v38, 16, v115
	v_and_b32_e32 v39, 0xffff0000, v115
	v_mul_f32_e32 v3, 0xbfb8aa3b, v3
	v_mul_f32_e32 v9, 0xbfb8aa3b, v9
	v_mul_f32_e32 v38, 0xbfb8aa3b, v38
	v_mul_f32_e32 v39, 0xbfb8aa3b, v39
	v_min_f32_e32 v3, 0x42fc0000, v3
	v_min_f32_e32 v9, 0x42fc0000, v9
	v_min_f32_e32 v38, 0x42fc0000, v38
	v_min_f32_e32 v39, 0x42fc0000, v39
	v_exp_f32_e32 v3, v3
	v_exp_f32_e32 v9, v9
	v_exp_f32_e32 v38, v38
	v_exp_f32_e32 v39, v39
	v_add_f32_e32 v3, 1.0, v3
	v_add_f32_e32 v9, 1.0, v9
	v_add_f32_e32 v50, 1.0, v38
	v_add_f32_e32 v51, 1.0, v39
	v_rcp_f32_e32 v38, v3
	v_rcp_f32_e32 v39, v9
	v_rcp_f32_e32 v50, v50
	v_rcp_f32_e32 v51, v51
	v_lshlrev_b32_e32 v48, 16, v118
	v_and_b32_e32 v49, 0xffff0000, v118
	v_lshlrev_b32_e32 v36, 16, v119
	v_and_b32_e32 v37, 0xffff0000, v119
	v_lshlrev_b32_e32 v44, 16, v122
	v_and_b32_e32 v45, 0xffff0000, v122
	v_lshlrev_b32_e32 v46, 16, v123
	v_and_b32_e32 v47, 0xffff0000, v123
	s_waitcnt lgkmcnt(0)
	v_pk_fma_f32 v[34:35], v[8:9], v[24:25], v[40:41] op_sel_hi:[0,1,1]
	v_pk_fma_f32 v[40:41], v[8:9], v[26:27], v[42:43] op_sel_hi:[0,1,1]
	v_pk_fma_f32 v[236:237], v[236:237], v[48:49], v[44:45]
	v_pk_fma_f32 v[238:239], v[238:239], v[36:37], v[46:47]
	v_pk_fma_f32 v[236:237], v[34:35], v[38:39], v[236:237]
	v_pk_fma_f32 v[238:239], v[40:41], v[50:51], v[238:239]
	v_cvt_pk_bf16_f32 v250, v236, v237
	v_cvt_pk_bf16_f32 v251, v238, v239
	s_nop 1
	v_permlane32_swap_b32 v248, v250
	v_permlane32_swap_b32 v249, v251
	global_store_dwordx4 v[0:1], v[248:251], off offset:32
	s_waitcnt vmcnt(1)
	v_permlane32_swap_b32 v124, v126
	v_permlane32_swap_b32 v125, v127
	v_permlane32_swap_b32 v128, v130
	v_permlane32_swap_b32 v129, v131
	v_permlane32_swap_b32 v132, v134
	v_permlane32_swap_b32 v133, v135
	ds_read2st64_b32 v[40:41], v137 offset0:12 offset1:13
	ds_read2st64_b32 v[42:43], v137 offset0:14 offset1:15
	v_lshlrev_b32_e32 v3, 16, v124
	v_and_b32_e32 v9, 0xffff0000, v124
	v_lshlrev_b32_e32 v38, 16, v125
	v_and_b32_e32 v39, 0xffff0000, v125
	v_mul_f32_e32 v3, 0xbfb8aa3b, v3
	v_mul_f32_e32 v9, 0xbfb8aa3b, v9
	v_mul_f32_e32 v38, 0xbfb8aa3b, v38
	v_mul_f32_e32 v39, 0xbfb8aa3b, v39
	v_min_f32_e32 v3, 0x42fc0000, v3
	v_min_f32_e32 v9, 0x42fc0000, v9
	v_min_f32_e32 v38, 0x42fc0000, v38
	v_min_f32_e32 v39, 0x42fc0000, v39
	v_exp_f32_e32 v3, v3
	v_exp_f32_e32 v9, v9
	v_exp_f32_e32 v38, v38
	v_exp_f32_e32 v39, v39
	v_add_f32_e32 v3, 1.0, v3
	v_add_f32_e32 v9, 1.0, v9
	v_add_f32_e32 v50, 1.0, v38
	v_add_f32_e32 v51, 1.0, v39
	v_rcp_f32_e32 v38, v3
	v_rcp_f32_e32 v39, v9
	v_rcp_f32_e32 v50, v50
	v_rcp_f32_e32 v51, v51
	v_lshlrev_b32_e32 v48, 16, v128
	v_and_b32_e32 v49, 0xffff0000, v128
	v_lshlrev_b32_e32 v36, 16, v129
	v_and_b32_e32 v37, 0xffff0000, v129
	v_lshlrev_b32_e32 v44, 16, v132
	v_and_b32_e32 v45, 0xffff0000, v132
	v_lshlrev_b32_e32 v46, 16, v133
	v_and_b32_e32 v47, 0xffff0000, v133
	s_waitcnt lgkmcnt(0)
	v_pk_fma_f32 v[34:35], v[8:9], v[76:77], v[40:41] op_sel_hi:[0,1,1]
	v_pk_fma_f32 v[40:41], v[8:9], v[78:79], v[42:43] op_sel_hi:[0,1,1]
	v_pk_fma_f32 v[240:241], v[240:241], v[48:49], v[44:45]
	v_pk_fma_f32 v[242:243], v[242:243], v[36:37], v[46:47]
	v_pk_fma_f32 v[240:241], v[34:35], v[38:39], v[240:241]
	v_pk_fma_f32 v[242:243], v[40:41], v[50:51], v[242:243]
	v_cvt_pk_bf16_f32 v248, v240, v241
	v_cvt_pk_bf16_f32 v249, v242, v243
	ds_read2st64_b32 v[40:41], v137 offset0:28 offset1:29
	ds_read2st64_b32 v[42:43], v137 offset0:30 offset1:31
	v_lshlrev_b32_e32 v3, 16, v126
	v_and_b32_e32 v9, 0xffff0000, v126
	v_lshlrev_b32_e32 v38, 16, v127
	v_and_b32_e32 v39, 0xffff0000, v127
	v_mul_f32_e32 v3, 0xbfb8aa3b, v3
	v_mul_f32_e32 v9, 0xbfb8aa3b, v9
	v_mul_f32_e32 v38, 0xbfb8aa3b, v38
	v_mul_f32_e32 v39, 0xbfb8aa3b, v39
	v_min_f32_e32 v3, 0x42fc0000, v3
	v_min_f32_e32 v9, 0x42fc0000, v9
	v_min_f32_e32 v38, 0x42fc0000, v38
	v_min_f32_e32 v39, 0x42fc0000, v39
	v_exp_f32_e32 v3, v3
	v_exp_f32_e32 v9, v9
	v_exp_f32_e32 v38, v38
	v_exp_f32_e32 v39, v39
	v_add_f32_e32 v3, 1.0, v3
	v_add_f32_e32 v9, 1.0, v9
	v_add_f32_e32 v50, 1.0, v38
	v_add_f32_e32 v51, 1.0, v39
	v_rcp_f32_e32 v38, v3
	v_rcp_f32_e32 v39, v9
	v_rcp_f32_e32 v50, v50
	v_rcp_f32_e32 v51, v51
	v_lshlrev_b32_e32 v48, 16, v130
	v_and_b32_e32 v49, 0xffff0000, v130
	v_lshlrev_b32_e32 v36, 16, v131
	v_and_b32_e32 v37, 0xffff0000, v131
	v_lshlrev_b32_e32 v44, 16, v134
	v_and_b32_e32 v45, 0xffff0000, v134
	v_lshlrev_b32_e32 v46, 16, v135
	v_and_b32_e32 v47, 0xffff0000, v135
	s_waitcnt lgkmcnt(0)
	v_pk_fma_f32 v[34:35], v[8:9], v[28:29], v[40:41] op_sel_hi:[0,1,1]
	v_pk_fma_f32 v[40:41], v[8:9], v[30:31], v[42:43] op_sel_hi:[0,1,1]
	v_pk_fma_f32 v[244:245], v[244:245], v[48:49], v[44:45]
	v_pk_fma_f32 v[246:247], v[246:247], v[36:37], v[46:47]
	v_pk_fma_f32 v[244:245], v[34:35], v[38:39], v[244:245]
	v_pk_fma_f32 v[246:247], v[40:41], v[50:51], v[246:247]
	v_cvt_pk_bf16_f32 v250, v244, v245
	v_cvt_pk_bf16_f32 v251, v246, v247
	s_nop 1
	v_permlane32_swap_b32 v248, v250
	v_permlane32_swap_b32 v249, v251
	global_store_dwordx4 v[0:1], v[248:251], off offset:48
